# weight-conversion tiles in the mixer phases: the four row loads of a tile are issued together (v224..v235) instead of one per memory round trip
# speedup vs baseline: 1.0819x; 1.0088x over previous
; DI void conv_tile(const float* __restrict__ src, int N, u16* __restrict__ dst, int ldd, int k0, int n0, int mode,
;                   const float* __restrict__ kscale, float* tl) {
;   const int t = get_tid();
;   const int r = t >> 4, c4 = (t & 15) * 4;
; #pragma unroll
;   for (int i = 0; i < 4; ++i) {
;     const int k = r + 16 * i;
;     float4 v = make_float4(0.f, 0.f, 0.f, 0.f);
;     if (n0 + c4 < N) v = *(const float4*)(src + (size_t)(k0 + k) * N + n0 + c4);
;     if (kscale) { const float s = kscale[k0 + k]; v.x *= s; v.y *= s; v.z *= s; v.w *= s; }
;     float* q = tl + k * 65 + c4;
;     q[0] = v.x; q[1] = v.y; q[2] = v.z; q[3] = v.w;
;   }
;   __syncthreads();
;   const int n = t >> 2, ks = (t & 3) * 16;
;   unsigned w[8];
; #pragma unroll
;   for (int j = 0; j < 8; ++j) w[j] = pack2(tl[(ks + 2 * j) * 65 + n], tl[(ks + 2 * j + 1) * 65 + n]);
;   const int nn = n0 + n;
;   const int drow = mode == 0 ? nn : ((nn >> 5) * 64 + (nn & 31) + (mode == 2 ? 32 : 0));
;   uint4* d = (uint4*)(dst + (size_t)drow * ldd + k0 + ks);
;   d[0] = make_uint4(w[0], w[1], w[2], w[3]);
;   d[1] = make_uint4(w[4], w[5], w[6], w[7]);
;   __syncthreads();
; }
; DI void convert_weights(const P& p, int layer, char* smem, int vb, int nvb, int part) {
;     ...
;     j -= nKV;
;     {
;       const float* src = layer == 0 ? p.ev_w_out : p.od_w_out;
;       conv_tile(src, 1024, (u16*)(ws + OFF_WOUT), 1024, (j / 16) * 64, (j % 16) * 64, 0, nullptr, tl);
;     }
.LBB0_736:
	s_cmpk_lt_i32 s15, 0x840
	s_movk_i32 s0, 0x840
	s_cselect_b32 s4, s0, 0xaa0
	s_add_i32 s4, s4, s15
	s_cmpk_gt_i32 s4, 0x107f
	s_mov_b64 s[0:1], -1
	s_cbranch_scc0 .LBB0_750
	s_add_i32 s5, s4, 0xffffef80
	s_cmpk_gt_u32 s5, 0x25f
	s_cbranch_scc0 .LBB0_739
	s_add_i32 s0, s4, 0xffffed20
	s_lshl_b32 s1, s0, 2
	s_lshl_b32 s0, s0, 6
	s_and_b32 s17, s0, 0x3c0
	s_waitcnt vmcnt(1)
	v_mov_b32_e32 v8, v132
	s_and_b32 s16, s1, 0x7fffffc0
	s_lshl_b32 s0, s17, 2
	v_ashrrev_i32_e32 v9, 4, v8
	v_lshlrev_b32_e32 v10, 4, v8
	s_add_u32 s0, s66, s0
	v_add_u32_e32 v6, s16, v9
	v_and_b32_e32 v0, 0xf0, v10
	s_addc_u32 s1, s67, 0
	v_mov_b32_e32 v1, v96
	v_ashrrev_i32_e32 v7, 31, v6
	v_lshl_add_u64 v[4:5], s[0:1], 0, v[0:1]
	v_lshlrev_b64 v[2:3], 12, v[6:7]
	s_movk_i32 s0, 0x104
	v_lshl_add_u64 v[2:3], v[4:5], 0, v[2:3]
	v_mul_lo_u32 v1, v9, s0
	v_add3_u32 v7, 0, v0, v1
	global_load_dwordx4 v[0:3], v[2:3], off
	v_add_u32_e32 v236, 16, v6
	v_ashrrev_i32_e32 v237, 31, v236
	v_lshlrev_b64 v[236:237], 12, v[236:237]
	v_lshl_add_u64 v[236:237], v[4:5], 0, v[236:237]
	global_load_dwordx4 v[224:227], v[236:237], off
	v_add_u32_e32 v236, 32, v6
	v_ashrrev_i32_e32 v237, 31, v236
	v_lshlrev_b64 v[236:237], 12, v[236:237]
	v_lshl_add_u64 v[236:237], v[4:5], 0, v[236:237]
	global_load_dwordx4 v[228:231], v[236:237], off
	v_add_u32_e32 v236, 48, v6
	v_ashrrev_i32_e32 v237, 31, v236
	v_lshlrev_b64 v[236:237], 12, v[236:237]
	v_lshl_add_u64 v[236:237], v[4:5], 0, v[236:237]
	global_load_dwordx4 v[232:235], v[236:237], off
	v_add_u32_e32 v9, 0x1040, v7
	v_and_b32_e32 v10, 48, v10
	v_ashrrev_i32_e32 v11, 2, v8
	v_readlane_b32 s0, v221, 31
	v_readlane_b32 s1, v221, 32
	s_lshl_b32 s20, s16, 1
	s_waitcnt vmcnt(3)
	ds_write2_b32 v7, v0, v1 offset1:1
	ds_write2_b32 v7, v2, v3 offset0:2 offset1:3
	s_waitcnt vmcnt(2)
	ds_write2_b32 v9, v224, v225 offset1:1
	v_add_u32_e32 v0, 0x1048, v7
	ds_write2_b32 v0, v226, v227 offset1:1
	v_add_u32_e32 v9, 0x2080, v7
	s_waitcnt vmcnt(1)
	ds_write2_b32 v9, v228, v229 offset1:1
	v_add_u32_e32 v0, 0x2088, v7
	ds_write2_b32 v0, v230, v231 offset1:1
	v_add_u32_e32 v4, 0x30c0, v7
	s_waitcnt vmcnt(0)
	ds_write2_b32 v4, v232, v233 offset1:1
	v_add_u32_e32 v0, 0x30c8, v7
	ds_write2_b32 v0, v234, v235 offset1:1
	v_mul_u32_u24_e32 v0, 0x41, v10
	v_and_b32_e32 v2, -4, v8
	v_lshlrev_b32_e32 v3, 2, v0
	v_add3_u32 v8, 0, v2, v3
	v_add3_u32 v9, 0, v3, v2
	s_waitcnt lgkmcnt(0)
	s_barrier
	ds_read2_b32 v[0:1], v8 offset1:130
	ds_read2_b32 v[2:3], v9 offset0:65 offset1:195
	v_add_u32_e32 v4, 0x400, v9
	ds_read2_b32 v[4:5], v4 offset0:69 offset1:199
	v_add_u32_e32 v6, 0x800, v9
	ds_read2_b32 v[6:7], v6 offset0:73 offset1:203
	s_waitcnt lgkmcnt(2)
	v_cvt_pk_bf16_f32 v0, v0, v2
	v_add_u32_e32 v2, 0x400, v8
	v_cvt_pk_bf16_f32 v1, v1, v3
	ds_read2_b32 v[2:3], v2 offset0:4 offset1:134
	v_lshlrev_b32_e32 v10, 1, v10
	s_waitcnt lgkmcnt(0)
	v_cvt_pk_bf16_f32 v2, v2, v4
	v_add_u32_e32 v4, 0x800, v8
	v_cvt_pk_bf16_f32 v3, v3, v5
	ds_read2_b32 v[4:5], v4 offset0:8 offset1:138
	s_waitcnt lgkmcnt(0)
	v_cvt_pk_bf16_f32 v4, v4, v6
	v_add_u32_e32 v6, 0xc00, v8
	v_add_u32_e32 v8, 0xc00, v9
	v_cvt_pk_bf16_f32 v5, v5, v7
	ds_read2_b32 v[6:7], v6 offset0:12 offset1:142
	ds_read2_b32 v[8:9], v8 offset0:77 offset1:207
	s_waitcnt lgkmcnt(0)
	v_cvt_pk_bf16_f32 v6, v6, v8
	v_add_u32_e32 v8, s17, v11
	v_cvt_pk_bf16_f32 v7, v7, v9
	v_ashrrev_i32_e32 v9, 31, v8
	v_lshlrev_b64 v[8:9], 11, v[8:9]
	v_lshl_add_u64 v[8:9], s[0:1], 0, v[8:9]
	v_lshl_add_u64 v[8:9], v[8:9], 0, s[20:21]
	v_mov_b32_e32 v11, v96
	v_lshl_add_u64 v[8:9], v[8:9], 0, v[10:11]
	global_store_dwordx4 v[8:9], v[0:3], off
	global_store_dwordx4 v[8:9], v[4:7], off offset:16
	s_barrier
	s_mov_b64 s[0:1], 0

; DI void conv_tile(const float* __restrict__ src, int N, u16* __restrict__ dst, int ldd, int k0, int n0, int mode,
;                   const float* __restrict__ kscale, float* tl) {
;   const int t = get_tid();
;   const int r = t >> 4, c4 = (t & 15) * 4;
; #pragma unroll
;   for (int i = 0; i < 4; ++i) {
;     const int k = r + 16 * i;
;     float4 v = make_float4(0.f, 0.f, 0.f, 0.f);
;     if (n0 + c4 < N) v = *(const float4*)(src + (size_t)(k0 + k) * N + n0 + c4);
;     if (kscale) { const float s = kscale[k0 + k]; v.x *= s; v.y *= s; v.z *= s; v.w *= s; }
;     float* q = tl + k * 65 + c4;
;     q[0] = v.x; q[1] = v.y; q[2] = v.z; q[3] = v.w;
;   }
;   __syncthreads();
;   const int n = t >> 2, ks = (t & 3) * 16;
;   unsigned w[8];
; #pragma unroll
;   for (int j = 0; j < 8; ++j) w[j] = pack2(tl[(ks + 2 * j) * 65 + n], tl[(ks + 2 * j + 1) * 65 + n]);
;   const int nn = n0 + n;
;   const int drow = mode == 0 ? nn : ((nn >> 5) * 64 + (nn & 31) + (mode == 2 ? 32 : 0));
;   uint4* d = (uint4*)(dst + (size_t)drow * ldd + k0 + ks);
;   d[0] = make_uint4(w[0], w[1], w[2], w[3]);
;   d[1] = make_uint4(w[4], w[5], w[6], w[7]);
;   __syncthreads();
; }
; DI void convert_weights(const P& p, int layer, char* smem, int vb, int nvb, int part) {
;     ...
;       } else {
;         const float* src = p.ffn_d + woff;
;         u16* dst = (u16*)(ws + OFF_WDN) + (size_t)s * 1024 * 2816;
;         conv_tile(src, 1024, dst, 2816, (jj / 16) * 64, (jj % 16) * 64, 0, nullptr, tl);
.LBB0_750:
	s_andn2_b64 vcc, exec, s[0:1]
	s_cbranch_vccnz .LBB0_735
	s_mul_hi_i32 s0, s4, 0x3e0f83e1
	s_lshr_b32 s1, s0, 31
	s_ashr_i32 s18, s0, 9
	s_add_i32 s18, s18, s1
	s_mul_i32 s0, s18, 0x840
	s_sub_i32 s19, s4, s0
	s_mul_i32 s0, s19, 0xba3
	s_lshr_b32 s1, s0, 31
	s_ashr_i32 s16, s0, 21
	s_add_i32 s16, s16, s1
	s_mul_i32 s0, s16, 0x2c0
	s_sub_i32 s17, s19, s0
	s_mul_i32 s0, s18, 0x2c0000
	s_mul_hi_i32 s1, s18, 0x2c0000
	s_add_u32 s0, s0, 0x580000
	s_addc_u32 s1, s1, 0
	s_mov_b64 s[4:5], -1
	s_cmpk_gt_i32 s19, 0x57f
	s_sext_i32_i16 s38, s17
	s_cbranch_scc0 .LBB0_753
	v_readlane_b32 s76, v223, 6
	s_lshl_b64 s[4:5], s[0:1], 2
	v_readlane_b32 s78, v223, 8
	v_readlane_b32 s79, v223, 9
	s_add_u32 s20, s78, s4
	s_addc_u32 s39, s79, s5
	s_mul_i32 s4, s18, 0x580000
	v_readlane_b32 s40, v221, 10
	s_mul_hi_i32 s5, s18, 0x580000
	v_readlane_b32 s41, v221, 11
	s_add_u32 s4, s40, s4
	s_addc_u32 s5, s41, s5
	s_lshl_b32 s40, s38, 2
	s_and_b32 s42, s40, 0xfc0
	s_lshl_b32 s40, s38, 6
	s_and_b32 s43, s40, 0x3c0
	s_waitcnt vmcnt(1)
	v_mov_b32_e32 v8, v132
	s_lshl_b32 s40, s43, 2
	v_ashrrev_i32_e32 v9, 4, v8
	v_lshlrev_b32_e32 v10, 4, v8
	s_add_u32 s40, s20, s40
	v_add_u32_e32 v6, s42, v9
	v_and_b32_e32 v0, 0xf0, v10
	s_addc_u32 s41, s39, 0
	v_mov_b32_e32 v1, v96
	v_ashrrev_i32_e32 v7, 31, v6
	v_lshl_add_u64 v[4:5], s[40:41], 0, v[0:1]
	v_lshlrev_b64 v[2:3], 12, v[6:7]
	s_movk_i32 s20, 0x104
	v_lshl_add_u64 v[2:3], v[4:5], 0, v[2:3]
	v_mul_lo_u32 v1, v9, s20
	v_add3_u32 v7, 0, v0, v1
	global_load_dwordx4 v[0:3], v[2:3], off
	v_add_u32_e32 v236, 16, v6
	v_ashrrev_i32_e32 v237, 31, v236
	v_lshlrev_b64 v[236:237], 12, v[236:237]
	v_lshl_add_u64 v[236:237], v[4:5], 0, v[236:237]
	global_load_dwordx4 v[224:227], v[236:237], off
	v_add_u32_e32 v236, 32, v6
	v_ashrrev_i32_e32 v237, 31, v236
	v_lshlrev_b64 v[236:237], 12, v[236:237]
	v_lshl_add_u64 v[236:237], v[4:5], 0, v[236:237]
	global_load_dwordx4 v[228:231], v[236:237], off
	v_add_u32_e32 v236, 48, v6
	v_ashrrev_i32_e32 v237, 31, v236
	v_lshlrev_b64 v[236:237], 12, v[236:237]
	v_lshl_add_u64 v[236:237], v[4:5], 0, v[236:237]
	global_load_dwordx4 v[232:235], v[236:237], off
	v_add_u32_e32 v9, 0x1040, v7
	v_and_b32_e32 v10, 48, v10
	v_ashrrev_i32_e32 v11, 2, v8
	v_add_u32_e32 v11, s43, v11
	s_lshl_b32 s20, s42, 1
	v_readlane_b32 s77, v223, 7
	v_readlane_b32 s80, v223, 10
	v_readlane_b32 s81, v223, 11
	v_readlane_b32 s82, v223, 12
	v_readlane_b32 s83, v223, 13
	v_readlane_b32 s84, v223, 14
	v_readlane_b32 s85, v223, 15
	v_readlane_b32 s86, v223, 16
	v_readlane_b32 s87, v223, 17
	v_readlane_b32 s88, v223, 18
	v_readlane_b32 s89, v223, 19
	v_readlane_b32 s90, v223, 20
	v_readlane_b32 s91, v223, 21
	s_waitcnt vmcnt(3)
	ds_write2_b32 v7, v0, v1 offset1:1
	ds_write2_b32 v7, v2, v3 offset0:2 offset1:3
	s_waitcnt vmcnt(2)
	ds_write2_b32 v9, v224, v225 offset1:1
	v_add_u32_e32 v0, 0x1048, v7
	ds_write2_b32 v0, v226, v227 offset1:1
	v_add_u32_e32 v9, 0x2080, v7
	s_waitcnt vmcnt(1)
	ds_write2_b32 v9, v228, v229 offset1:1
	v_add_u32_e32 v0, 0x2088, v7
	ds_write2_b32 v0, v230, v231 offset1:1
	v_add_u32_e32 v4, 0x30c0, v7
	s_waitcnt vmcnt(0)
	ds_write2_b32 v4, v232, v233 offset1:1
	v_add_u32_e32 v0, 0x30c8, v7
	ds_write2_b32 v0, v234, v235 offset1:1
	v_mul_u32_u24_e32 v0, 0x41, v10
	v_and_b32_e32 v2, -4, v8
	v_lshlrev_b32_e32 v3, 2, v0
	v_add3_u32 v8, 0, v2, v3
	v_add3_u32 v9, 0, v3, v2
	s_waitcnt lgkmcnt(0)
	s_barrier
	ds_read2_b32 v[0:1], v8 offset1:130
	ds_read2_b32 v[2:3], v9 offset0:65 offset1:195
	v_add_u32_e32 v4, 0x400, v9
	ds_read2_b32 v[4:5], v4 offset0:69 offset1:199
	v_add_u32_e32 v6, 0x800, v9
	ds_read2_b32 v[6:7], v6 offset0:73 offset1:203
	s_waitcnt lgkmcnt(2)
	v_cvt_pk_bf16_f32 v0, v0, v2
	v_add_u32_e32 v2, 0x400, v8
	v_cvt_pk_bf16_f32 v1, v1, v3
	ds_read2_b32 v[2:3], v2 offset0:4 offset1:134
	v_lshlrev_b32_e32 v10, 1, v10
	s_waitcnt lgkmcnt(0)
	v_cvt_pk_bf16_f32 v2, v2, v4
	v_add_u32_e32 v4, 0x800, v8
	v_cvt_pk_bf16_f32 v3, v3, v5
	ds_read2_b32 v[4:5], v4 offset0:8 offset1:138
	s_waitcnt lgkmcnt(0)
	v_cvt_pk_bf16_f32 v4, v4, v6
	v_add_u32_e32 v6, 0xc00, v8
	v_add_u32_e32 v8, 0xc00, v9
	v_cvt_pk_bf16_f32 v5, v5, v7
	ds_read2_b32 v[6:7], v6 offset0:12 offset1:142
	ds_read2_b32 v[8:9], v8 offset0:77 offset1:207
	s_waitcnt lgkmcnt(0)
	v_cvt_pk_bf16_f32 v6, v6, v8
	v_cvt_pk_bf16_f32 v7, v7, v9
	v_mov_b64_e32 v[8:9], s[4:5]
	s_movk_i32 s4, 0x1600
	v_mad_i64_i32 v[8:9], s[4:5], v11, s4, v[8:9]
	v_lshl_add_u64 v[8:9], v[8:9], 0, s[20:21]
	v_mov_b32_e32 v11, v96
	v_lshl_add_u64 v[8:9], v[8:9], 0, v[10:11]
	global_store_dwordx4 v[8:9], v[0:3], off
	global_store_dwordx4 v[8:9], v[4:7], off offset:16
	s_barrier
	s_mov_b64 s[4:5], 0
; DI void conv_tile(const float* __restrict__ src, int N, u16* __restrict__ dst, int ldd, int k0, int n0, int mode,
;                   const float* __restrict__ kscale, float* tl) {
;   const int t = get_tid();
;   const int r = t >> 4, c4 = (t & 15) * 4;
; #pragma unroll
;   for (int i = 0; i < 4; ++i) {
;     const int k = r + 16 * i;
;     float4 v = make_float4(0.f, 0.f, 0.f, 0.f);
;     if (n0 + c4 < N) v = *(const float4*)(src + (size_t)(k0 + k) * N + n0 + c4);
;     if (kscale) { const float s = kscale[k0 + k]; v.x *= s; v.y *= s; v.z *= s; v.w *= s; }
;     float* q = tl + k * 65 + c4;
;     q[0] = v.x; q[1] = v.y; q[2] = v.z; q[3] = v.w;
;   }
;   __syncthreads();
;   const int n = t >> 2, ks = (t & 3) * 16;
;   unsigned w[8];
; #pragma unroll
;   for (int j = 0; j < 8; ++j) w[j] = pack2(tl[(ks + 2 * j) * 65 + n], tl[(ks + 2 * j + 1) * 65 + n]);
;   const int nn = n0 + n;
;   const int drow = mode == 0 ? nn : ((nn >> 5) * 64 + (nn & 31) + (mode == 2 ? 32 : 0));
;   uint4* d = (uint4*)(dst + (size_t)drow * ldd + k0 + ks);
;   d[0] = make_uint4(w[0], w[1], w[2], w[3]);
;   d[1] = make_uint4(w[4], w[5], w[6], w[7]);
;   __syncthreads();
; }
; DI void convert_weights(const P& p, int layer, char* smem, int vb, int nvb, int part) {
;     ...
;       if (which < 2) {
;         const float* src = (which == 0 ? p.ffn_g : p.ffn_u) + woff;
;         u16* dst = (u16*)(ws + OFF_WGU) + (size_t)s * 5632 * 1024;
;         conv_tile(src, 2816, dst, 1024, (jj / 44) * 64, (jj % 44) * 64, 1 + which, nullptr, tl);
.LBB0_753:
	s_andn2_b64 vcc, exec, s[4:5]
	s_cbranch_vccnz .LBB0_735
	v_readlane_b32 s76, v223, 22
	v_readlane_b32 s77, v223, 23
	v_readlane_b32 s78, v223, 24
	v_readlane_b32 s79, v223, 25
	v_readlane_b32 s80, v223, 26
	v_readlane_b32 s81, v223, 27
	v_readlane_b32 s82, v223, 28
	v_readlane_b32 s83, v223, 29
	v_readlane_b32 s84, v223, 30
	v_readlane_b32 s85, v223, 31
	v_readlane_b32 s86, v223, 32
	v_readlane_b32 s87, v223, 33
	v_readlane_b32 s88, v223, 34
	v_readlane_b32 s89, v223, 35
	s_addk_i32 s19, 0x2bf
	v_readlane_b32 s90, v223, 36
	v_readlane_b32 s91, v223, 37
	s_mov_b64 s[52:53], s[88:89]
	v_readlane_b32 s72, v223, 6
	s_cmpk_lt_u32 s19, 0x57f
	s_mov_b64 s[54:55], s[90:91]
	v_readlane_b32 s73, v223, 7
	s_cselect_b32 s4, s55, s73
	s_cselect_b32 s5, s54, s72
	s_lshl_b64 s[0:1], s[0:1], 2
	s_add_u32 s19, s5, s0
	s_addc_u32 s20, s4, s1
	s_mul_hi_i32 s1, s18, 0xb00000
	s_mul_i32 s18, s18, 0xb00000
	s_add_u32 s0, s70, s18
	s_mulk_i32 s38, 0xba3
	s_addc_u32 s1, s71, s1
	s_lshr_b32 s4, s38, 31
	s_ashr_i32 s5, s38, 17
	s_add_i32 s5, s5, s4
	s_sext_i32_i16 s4, s5
	s_mul_i32 s5, s5, 44
	s_sub_i32 s5, s17, s5
	s_sext_i32_i16 s5, s5
	s_add_i32 s16, s16, 1
	s_lshl_b32 s4, s4, 6
	s_lshl_b32 s38, s5, 6
	s_and_b32 s5, s16, 0xffff
	s_cmp_eq_u32 s5, 0
	s_cselect_b64 vcc, -1, 0
	s_ashr_i32 s39, s38, 31
	s_waitcnt vmcnt(2)
	v_mov_b32_e32 v6, v132
	s_lshl_b64 s[16:17], s[38:39], 2
	s_add_u32 s16, s19, s16
	s_waitcnt vmcnt(1)
	v_lshlrev_b32_e32 v8, 4, v6
	v_ashrrev_i32_e32 v7, 4, v6
	v_and_b32_e32 v0, 0xf0, v8
	s_addc_u32 s17, s20, s17
	v_mov_b32_e32 v1, v96
	v_lshl_add_u64 v[4:5], s[16:17], 0, v[0:1]
	v_add_u32_e32 v9, s4, v7
	s_movk_i32 s18, 0x2c00
	v_mad_i64_i32 v[2:3], s[16:17], v9, s18, v[4:5]
	s_movk_i32 s16, 0x104
	s_nop 0
	v_mul_lo_u32 v1, v7, s16
	v_add3_u32 v7, 0, v0, v1
	global_load_dwordx4 v[0:3], v[2:3], off
	v_add_u32_e32 v236, 16, v9
	v_mad_i64_i32 v[236:237], s[16:17], v236, s18, v[4:5]
	global_load_dwordx4 v[224:227], v[236:237], off
	v_add_u32_e32 v236, 32, v9
	v_mad_i64_i32 v[236:237], s[16:17], v236, s18, v[4:5]
	global_load_dwordx4 v[228:231], v[236:237], off
	v_add_u32_e32 v236, 48, v9
	v_mad_i64_i32 v[236:237], s[16:17], v236, s18, v[4:5]
	global_load_dwordx4 v[232:235], v[236:237], off
	v_add_u32_e32 v10, 0x1040, v7
	v_and_b32_e32 v11, 48, v8
	s_cmp_eq_u32 s5, 2
	s_cselect_b32 s5, 32, 0
	v_readlane_b32 s54, v218, 44
	v_readlane_b32 s74, v223, 8
	v_readlane_b32 s75, v223, 9
	v_readlane_b32 s76, v223, 10
	v_readlane_b32 s77, v223, 11
	v_readlane_b32 s78, v223, 12
	v_readlane_b32 s79, v223, 13
	v_readlane_b32 s80, v223, 14
	v_readlane_b32 s81, v223, 15
	v_readlane_b32 s82, v223, 16
	v_readlane_b32 s83, v223, 17
	v_readlane_b32 s84, v223, 18
	v_readlane_b32 s85, v223, 19
	v_readlane_b32 s86, v223, 20
	v_readlane_b32 s87, v223, 21
	s_waitcnt vmcnt(3)
	ds_write2_b32 v7, v0, v1 offset1:1
	ds_write2_b32 v7, v2, v3 offset0:2 offset1:3
	s_waitcnt vmcnt(2)
	ds_write2_b32 v10, v224, v225 offset1:1
	v_add_u32_e32 v0, 0x1048, v7
	ds_write2_b32 v0, v226, v227 offset1:1
	v_add_u32_e32 v10, 0x2080, v7
	s_waitcnt vmcnt(1)
	ds_write2_b32 v10, v228, v229 offset1:1
	v_add_u32_e32 v0, 0x2088, v7
	ds_write2_b32 v0, v230, v231 offset1:1
	v_add_u32_e32 v4, 0x30c0, v7
	v_ashrrev_i32_e32 v10, 2, v6
	s_waitcnt vmcnt(0)
	ds_write2_b32 v4, v232, v233 offset1:1
	v_add_u32_e32 v0, 0x30c8, v7
	ds_write2_b32 v0, v234, v235 offset1:1
	v_mul_u32_u24_e32 v0, 0x41, v11
	v_and_b32_e32 v2, -4, v6
	v_lshlrev_b32_e32 v3, 2, v0
	v_add3_u32 v8, 0, v2, v3
	v_add3_u32 v9, 0, v3, v2
	s_waitcnt lgkmcnt(0)
	s_barrier
	ds_read2_b32 v[0:1], v8 offset1:130
	ds_read2_b32 v[2:3], v9 offset0:65 offset1:195
	v_add_u32_e32 v4, 0x400, v9
	ds_read2_b32 v[4:5], v4 offset0:69 offset1:199
	v_add_u32_e32 v6, 0x800, v9
	ds_read2_b32 v[6:7], v6 offset0:73 offset1:203
	s_waitcnt lgkmcnt(2)
	v_cvt_pk_bf16_f32 v0, v0, v2
	v_add_u32_e32 v2, 0x400, v8
	v_cvt_pk_bf16_f32 v1, v1, v3
	ds_read2_b32 v[2:3], v2 offset0:4 offset1:134
	s_waitcnt lgkmcnt(0)
	v_cvt_pk_bf16_f32 v2, v2, v4
	v_add_u32_e32 v4, 0x800, v8
	v_cvt_pk_bf16_f32 v3, v3, v5
	ds_read2_b32 v[4:5], v4 offset0:8 offset1:138
	s_waitcnt lgkmcnt(0)
	v_cvt_pk_bf16_f32 v4, v4, v6
	v_add_u32_e32 v6, 0xc00, v8
	v_add_u32_e32 v8, 0xc00, v9
	v_cvt_pk_bf16_f32 v5, v5, v7
	ds_read2_b32 v[6:7], v6 offset0:12 offset1:142
	ds_read2_b32 v[8:9], v8 offset0:77 offset1:207
	s_waitcnt lgkmcnt(0)
	v_cvt_pk_bf16_f32 v6, v6, v8
	v_add_u32_e32 v8, s38, v10
	v_cvt_pk_bf16_f32 v7, v7, v9
	v_lshlrev_b32_e32 v9, 1, v8
	v_and_b32_e32 v9, 0xffffffc0, v9
	v_and_b32_e32 v10, 31, v10
	v_or3_b32 v9, v10, s5, v9
	v_cndmask_b32_e32 v8, v9, v8, vcc
	v_ashrrev_i32_e32 v9, 31, v8
	v_lshlrev_b64 v[8:9], 11, v[8:9]
	v_lshl_add_u64 v[8:9], s[0:1], 0, v[8:9]
	s_ashr_i32 s5, s4, 31
	v_lshl_add_u64 v[8:9], s[4:5], 1, v[8:9]
	v_lshlrev_b32_e32 v10, 1, v11
	v_mov_b32_e32 v11, v96
	v_lshl_add_u64 v[8:9], v[8:9], 0, v[10:11]
	global_store_dwordx4 v[8:9], v[0:3], off
	global_store_dwordx4 v[8:9], v[4:7], off offset:16
	s_barrier
	s_branch .LBB0_735

; DI void conv_tile(const float* __restrict__ src, int N, u16* __restrict__ dst, int ldd, int k0, int n0, int mode,
;                   const float* __restrict__ kscale, float* tl) {
;   const int t = get_tid();
;   const int r = t >> 4, c4 = (t & 15) * 4;
; #pragma unroll
;   for (int i = 0; i < 4; ++i) {
;     const int k = r + 16 * i;
;     float4 v = make_float4(0.f, 0.f, 0.f, 0.f);
;     if (n0 + c4 < N) v = *(const float4*)(src + (size_t)(k0 + k) * N + n0 + c4);
;     if (kscale) { const float s = kscale[k0 + k]; v.x *= s; v.y *= s; v.z *= s; v.w *= s; }
;     float* q = tl + k * 65 + c4;
;     q[0] = v.x; q[1] = v.y; q[2] = v.z; q[3] = v.w;
;   }
;   __syncthreads();
;   const int n = t >> 2, ks = (t & 3) * 16;
;   unsigned w[8];
; #pragma unroll
;   for (int j = 0; j < 8; ++j) w[j] = pack2(tl[(ks + 2 * j) * 65 + n], tl[(ks + 2 * j + 1) * 65 + n]);
;   const int nn = n0 + n;
;   const int drow = mode == 0 ? nn : ((nn >> 5) * 64 + (nn & 31) + (mode == 2 ? 32 : 0));
;   uint4* d = (uint4*)(dst + (size_t)drow * ldd + k0 + ks);
;   d[0] = make_uint4(w[0], w[1], w[2], w[3]);
;   d[1] = make_uint4(w[4], w[5], w[6], w[7]);
;   __syncthreads();
; }
; DI void convert_weights(const P& p, int layer, char* smem, int vb, int nvb, int part) {
;     ...
;     j -= nKV;
;     {
;       const float* src = layer == 0 ? p.ev_w_out : p.od_w_out;
;       conv_tile(src, 1024, (u16*)(ws + OFF_WOUT), 1024, (j / 16) * 64, (j % 16) * 64, 0, nullptr, tl);
;     }
.LBB0_1112:
	s_cmpk_lt_i32 s40, 0x840
	s_movk_i32 s0, 0xb88
	s_cselect_b32 s15, 0x840, s0
	s_add_i32 s15, s15, s40
	s_cmpk_gt_i32 s15, 0x107f
	s_mov_b64 s[0:1], -1
	s_cbranch_scc0 .LBB0_1150
	s_add_i32 s4, s15, 0xffffef80
	s_cmpk_gt_u32 s4, 0x2bf
	s_cbranch_scc0 .LBB0_1139
	s_add_i32 s5, s15, 0xffffecc0
	s_cmpk_gt_u32 s5, 0x47
	s_cbranch_scc0 .LBB0_1128
	s_add_i32 s16, s15, 0xffffec78
	s_cmp_gt_u32 s16, 63
	s_cbranch_scc0 .LBB0_1117
	s_lshl_b32 s0, s15, 2
	s_add_i32 s0, s0, 0x7fffb0e0
	s_and_b32 s17, s0, 0x7fffffc0
	s_lshl_b32 s0, s16, 6
	s_and_b32 s18, s0, 0x3c0
	v_mov_b32_e32 v8, v132
	v_readlane_b32 s72, v223, 38
	s_lshl_b32 s0, s18, 2
	v_ashrrev_i32_e32 v9, 4, v8
	v_readlane_b32 s82, v223, 48
	v_lshlrev_b32_e32 v10, 4, v8
	v_readlane_b32 s83, v223, 49
	s_add_u32 s0, s82, s0
	v_add_u32_e32 v6, s17, v9
	v_and_b32_e32 v0, 0xf0, v10
	s_addc_u32 s1, s83, 0
	v_mov_b32_e32 v1, v96
	v_ashrrev_i32_e32 v7, 31, v6
	v_lshl_add_u64 v[4:5], s[0:1], 0, v[0:1]
	v_lshlrev_b64 v[2:3], 12, v[6:7]
	s_movk_i32 s0, 0x104
	v_lshl_add_u64 v[2:3], v[4:5], 0, v[2:3]
	v_mul_lo_u32 v1, v9, s0
	v_add3_u32 v7, 0, v0, v1
	global_load_dwordx4 v[0:3], v[2:3], off
	v_add_u32_e32 v236, 16, v6
	v_ashrrev_i32_e32 v237, 31, v236
	v_lshlrev_b64 v[236:237], 12, v[236:237]
	v_lshl_add_u64 v[236:237], v[4:5], 0, v[236:237]
	global_load_dwordx4 v[224:227], v[236:237], off
	v_add_u32_e32 v236, 32, v6
	v_ashrrev_i32_e32 v237, 31, v236
	v_lshlrev_b64 v[236:237], 12, v[236:237]
	v_lshl_add_u64 v[236:237], v[4:5], 0, v[236:237]
	global_load_dwordx4 v[228:231], v[236:237], off
	v_add_u32_e32 v236, 48, v6
	v_ashrrev_i32_e32 v237, 31, v236
	v_lshlrev_b64 v[236:237], 12, v[236:237]
	v_lshl_add_u64 v[236:237], v[4:5], 0, v[236:237]
	global_load_dwordx4 v[232:235], v[236:237], off
	v_add_u32_e32 v9, 0x1040, v7
	v_and_b32_e32 v10, 48, v10
	v_ashrrev_i32_e32 v11, 2, v8
	v_readlane_b32 s0, v221, 31
	v_readlane_b32 s1, v221, 32
	s_lshl_b32 s20, s17, 1
	v_readlane_b32 s73, v223, 39
	v_readlane_b32 s74, v223, 40
	v_readlane_b32 s75, v223, 41
	v_readlane_b32 s76, v223, 42
	v_readlane_b32 s77, v223, 43
	v_readlane_b32 s78, v223, 44
	v_readlane_b32 s79, v223, 45
	v_readlane_b32 s80, v223, 46
	v_readlane_b32 s81, v223, 47
	v_readlane_b32 s84, v223, 50
	v_readlane_b32 s85, v223, 51
	v_readlane_b32 s86, v223, 52
	v_readlane_b32 s87, v223, 53
	s_waitcnt vmcnt(3)
	ds_write2_b32 v7, v0, v1 offset1:1
	ds_write2_b32 v7, v2, v3 offset0:2 offset1:3
	s_waitcnt vmcnt(2)
	ds_write2_b32 v9, v224, v225 offset1:1
	v_add_u32_e32 v0, 0x1048, v7
	ds_write2_b32 v0, v226, v227 offset1:1
	v_add_u32_e32 v9, 0x2080, v7
	s_waitcnt vmcnt(1)
	ds_write2_b32 v9, v228, v229 offset1:1
	v_add_u32_e32 v0, 0x2088, v7
	ds_write2_b32 v0, v230, v231 offset1:1
	v_add_u32_e32 v4, 0x30c0, v7
	s_waitcnt vmcnt(0)
	ds_write2_b32 v4, v232, v233 offset1:1
	v_add_u32_e32 v0, 0x30c8, v7
	ds_write2_b32 v0, v234, v235 offset1:1
	v_mul_u32_u24_e32 v0, 0x41, v10
	v_and_b32_e32 v2, -4, v8
	v_lshlrev_b32_e32 v3, 2, v0
	v_add3_u32 v8, 0, v2, v3
	v_add3_u32 v9, 0, v3, v2
	s_waitcnt lgkmcnt(0)
	s_barrier
	ds_read2_b32 v[0:1], v8 offset1:130
	ds_read2_b32 v[2:3], v9 offset0:65 offset1:195
	v_add_u32_e32 v4, 0x400, v9
	ds_read2_b32 v[4:5], v4 offset0:69 offset1:199
	v_add_u32_e32 v6, 0x800, v9
	ds_read2_b32 v[6:7], v6 offset0:73 offset1:203
	s_waitcnt lgkmcnt(2)
	v_cvt_pk_bf16_f32 v0, v0, v2
	v_add_u32_e32 v2, 0x400, v8
	v_cvt_pk_bf16_f32 v1, v1, v3
	ds_read2_b32 v[2:3], v2 offset0:4 offset1:134
	v_lshlrev_b32_e32 v10, 1, v10
	s_waitcnt lgkmcnt(0)
	v_cvt_pk_bf16_f32 v2, v2, v4
	v_add_u32_e32 v4, 0x800, v8
	v_cvt_pk_bf16_f32 v3, v3, v5
	ds_read2_b32 v[4:5], v4 offset0:8 offset1:138
	s_waitcnt lgkmcnt(0)
	v_cvt_pk_bf16_f32 v4, v4, v6
	v_add_u32_e32 v6, 0xc00, v8
	v_add_u32_e32 v8, 0xc00, v9
	v_cvt_pk_bf16_f32 v5, v5, v7
	ds_read2_b32 v[6:7], v6 offset0:12 offset1:142
	ds_read2_b32 v[8:9], v8 offset0:77 offset1:207
	s_waitcnt lgkmcnt(0)
	v_cvt_pk_bf16_f32 v6, v6, v8
	v_add_u32_e32 v8, s18, v11
	v_cvt_pk_bf16_f32 v7, v7, v9
	v_ashrrev_i32_e32 v9, 31, v8
	v_lshlrev_b64 v[8:9], 11, v[8:9]
	v_lshl_add_u64 v[8:9], s[0:1], 0, v[8:9]
	v_lshl_add_u64 v[8:9], v[8:9], 0, s[20:21]
	v_mov_b32_e32 v11, v96
	v_lshl_add_u64 v[8:9], v[8:9], 0, v[10:11]
	global_store_dwordx4 v[8:9], v[0:3], off
	global_store_dwordx4 v[8:9], v[4:7], off offset:16
	s_barrier
	s_mov_b64 s[0:1], 0
; DI void conv_tile(const float* __restrict__ src, int N, u16* __restrict__ dst, int ldd, int k0, int n0, int mode,
;                   const float* __restrict__ kscale, float* tl) {
;   const int t = get_tid();
;   const int r = t >> 4, c4 = (t & 15) * 4;
; #pragma unroll
;   for (int i = 0; i < 4; ++i) {
;     const int k = r + 16 * i;
;     float4 v = make_float4(0.f, 0.f, 0.f, 0.f);
;     if (n0 + c4 < N) v = *(const float4*)(src + (size_t)(k0 + k) * N + n0 + c4);
;     if (kscale) { const float s = kscale[k0 + k]; v.x *= s; v.y *= s; v.z *= s; v.w *= s; }
;     float* q = tl + k * 65 + c4;
;     q[0] = v.x; q[1] = v.y; q[2] = v.z; q[3] = v.w;
;   }
;   __syncthreads();
;   const int n = t >> 2, ks = (t & 3) * 16;
;   unsigned w[8];
; #pragma unroll
;   for (int j = 0; j < 8; ++j) w[j] = pack2(tl[(ks + 2 * j) * 65 + n], tl[(ks + 2 * j + 1) * 65 + n]);
;   const int nn = n0 + n;
;   const int drow = mode == 0 ? nn : ((nn >> 5) * 64 + (nn & 31) + (mode == 2 ? 32 : 0));
;   uint4* d = (uint4*)(dst + (size_t)drow * ldd + k0 + ks);
;   d[0] = make_uint4(w[0], w[1], w[2], w[3]);
;   d[1] = make_uint4(w[4], w[5], w[6], w[7]);
;   __syncthreads();
; }
; DI void convert_weights(const P& p, int layer, char* smem, int vb, int nvb, int part) {
;     ...
;     if (j < nKV) {
;       conv_tile(p.ev_w_kv_up, 1024, (u16*)(ws + OFF_WKVUP), 256, (j / 16) * 64, (j % 16) * 64, 0, p.ev_kv_a_norm, tl);
.LBB0_1117:
	s_andn2_b64 vcc, exec, s[0:1]
	s_cbranch_vccnz .LBB0_1127
	s_lshl_b32 s0, s16, 2
	s_and_b32 s17, s0, 0xc0
	s_lshl_b32 s0, s16, 6
	s_and_b32 s16, s0, 0x3c0
	v_mov_b32_e32 v10, v132
	v_readlane_b32 s76, v223, 6
	s_lshl_b32 s0, s16, 2
	v_ashrrev_i32_e32 v11, 4, v10
	v_lshlrev_b32_e32 v0, 2, v10
	v_readlane_b32 s88, v223, 18
	v_and_b32_e32 v12, 60, v0
	v_readlane_b32 s89, v223, 19
	s_add_u32 s0, s88, s0
	v_add_u32_e32 v8, s17, v11
	s_addc_u32 s1, s89, 0
	v_lshlrev_b32_e32 v0, 2, v12
	v_mov_b32_e32 v1, v96
	v_ashrrev_i32_e32 v9, 31, v8
	v_lshl_add_u64 v[6:7], s[0:1], 0, v[0:1]
	v_lshlrev_b64 v[0:1], 12, v[8:9]
	v_lshl_add_u64 v[0:1], v[6:7], 0, v[0:1]
	global_load_dwordx4 v[0:3], v[0:1], off
	v_add_u32_e32 v236, 16, v8
	v_ashrrev_i32_e32 v237, 31, v236
	v_lshlrev_b64 v[236:237], 12, v[236:237]
	v_lshl_add_u64 v[236:237], v[6:7], 0, v[236:237]
	global_load_dwordx4 v[224:227], v[236:237], off
	v_add_u32_e32 v236, 32, v8
	v_ashrrev_i32_e32 v237, 31, v236
	v_lshlrev_b64 v[236:237], 12, v[236:237]
	v_lshl_add_u64 v[236:237], v[6:7], 0, v[236:237]
	global_load_dwordx4 v[228:231], v[236:237], off
	v_add_u32_e32 v236, 48, v8
	v_ashrrev_i32_e32 v237, 31, v236
	v_lshlrev_b64 v[236:237], 12, v[236:237]
	v_lshl_add_u64 v[236:237], v[6:7], 0, v[236:237]
	global_load_dwordx4 v[232:235], v[236:237], off
	v_readlane_b32 s18, v220, 47
	v_readlane_b32 s19, v220, 48
	v_readlane_b32 s86, v223, 16
	v_readlane_b32 s87, v223, 17
	v_cndmask_b32_e64 v4, 0, 1, s[18:19]
	v_cmp_ne_u32_e64 s[0:1], 1, v4
	s_andn2_b64 vcc, exec, s[18:19]
	v_lshl_add_u64 v[4:5], v[8:9], 2, s[86:87]
	v_readlane_b32 s77, v223, 7
	v_readlane_b32 s78, v223, 8
	v_readlane_b32 s79, v223, 9
	v_readlane_b32 s80, v223, 10
	v_readlane_b32 s81, v223, 11
	v_readlane_b32 s82, v223, 12
	v_readlane_b32 s83, v223, 13
	v_readlane_b32 s84, v223, 14
	v_readlane_b32 s85, v223, 15
	v_readlane_b32 s90, v223, 20
	v_readlane_b32 s91, v223, 21
	s_cbranch_vccnz .LBB0_1120
	global_load_dword v14, v[4:5], off
	s_waitcnt vmcnt(0)
	v_pk_mul_f32 v[0:1], v[0:1], v[14:15] op_sel_hi:[1,0]
	v_pk_mul_f32 v[2:3], v[2:3], v[14:15] op_sel_hi:[1,0]
.LBB0_1120:
	s_movk_i32 s18, 0x104
	v_lshl_add_u32 v9, v12, 2, 0
	v_mul_lo_u32 v11, v11, s18
	v_add_u32_e32 v9, v9, v11
	s_waitcnt vmcnt(3)
	ds_write2_b32 v9, v0, v1 offset1:1
	ds_write2_b32 v9, v2, v3 offset0:2 offset1:3
	s_and_b64 vcc, exec, s[0:1]
	s_cbranch_vccnz .LBB0_1122
	global_load_dword v12, v[4:5], off offset:64
	s_waitcnt vmcnt(0)
	v_pk_mul_f32 v[224:225], v[224:225], v[12:13] op_sel_hi:[1, 0]
	v_pk_mul_f32 v[226:227], v[226:227], v[12:13] op_sel_hi:[1, 0]
.LBB0_1122:
	v_add_u32_e32 v11, 0x1040, v9
	s_waitcnt vmcnt(2)
	ds_write2_b32 v11, v224, v225 offset1:1
	v_add_u32_e32 v0, 0x1048, v9
	ds_write2_b32 v0, v226, v227 offset1:1
	s_and_b64 vcc, exec, s[0:1]
	s_cbranch_vccnz .LBB0_1124
	global_load_dword v12, v[4:5], off offset:128
	s_waitcnt vmcnt(0)
	v_pk_mul_f32 v[228:229], v[228:229], v[12:13] op_sel_hi:[1, 0]
	v_pk_mul_f32 v[230:231], v[230:231], v[12:13] op_sel_hi:[1, 0]
.LBB0_1124:
	v_add_u32_e32 v11, 0x2080, v9
	s_waitcnt vmcnt(1)
	ds_write2_b32 v11, v228, v229 offset1:1
	v_add_u32_e32 v0, 0x2088, v9
	ds_write2_b32 v0, v230, v231 offset1:1
	s_and_b64 vcc, exec, s[0:1]
	s_cbranch_vccnz .LBB0_1126
	global_load_dword v4, v[4:5], off offset:192
	s_waitcnt vmcnt(0)
	v_pk_mul_f32 v[232:233], v[232:233], v[4:5] op_sel_hi:[1, 0]
	v_pk_mul_f32 v[234:235], v[234:235], v[4:5] op_sel_hi:[1, 0]
.LBB0_1126:
	v_add_u32_e32 v4, 0x30c0, v9
	s_waitcnt vmcnt(0)
	ds_write2_b32 v4, v232, v233 offset1:1
	v_add_u32_e32 v0, 0x30c8, v9
	ds_write2_b32 v0, v234, v235 offset1:1
	v_lshlrev_b32_e32 v0, 4, v10
	v_and_b32_e32 v12, 48, v0
	v_mul_u32_u24_e32 v0, 0x41, v12
	v_and_b32_e32 v2, -4, v10
	v_lshlrev_b32_e32 v3, 2, v0
	v_add3_u32 v8, 0, v2, v3
	v_add3_u32 v9, 0, v3, v2
	s_waitcnt lgkmcnt(0)
	s_barrier
	ds_read2_b32 v[0:1], v8 offset1:130
	ds_read2_b32 v[2:3], v9 offset0:65 offset1:195
	v_add_u32_e32 v4, 0x400, v9
	ds_read2_b32 v[4:5], v4 offset0:69 offset1:199
	v_add_u32_e32 v6, 0x800, v9
	ds_read2_b32 v[6:7], v6 offset0:73 offset1:203
	s_waitcnt lgkmcnt(2)
	v_cvt_pk_bf16_f32 v0, v0, v2
	v_add_u32_e32 v2, 0x400, v8
	v_cvt_pk_bf16_f32 v1, v1, v3
	ds_read2_b32 v[2:3], v2 offset0:4 offset1:134
	v_ashrrev_i32_e32 v11, 2, v10
	v_readlane_b32 s0, v221, 48
	v_readlane_b32 s1, v221, 49
	s_lshl_b32 s20, s17, 1
	s_waitcnt lgkmcnt(0)
	v_cvt_pk_bf16_f32 v2, v2, v4
	v_add_u32_e32 v4, 0x800, v8
	v_cvt_pk_bf16_f32 v3, v3, v5
	ds_read2_b32 v[4:5], v4 offset0:8 offset1:138
	v_lshlrev_b32_e32 v10, 1, v12
	s_waitcnt lgkmcnt(0)
	v_cvt_pk_bf16_f32 v4, v4, v6
	v_add_u32_e32 v6, 0xc00, v8
	v_add_u32_e32 v8, 0xc00, v9
	v_cvt_pk_bf16_f32 v5, v5, v7
	ds_read2_b32 v[6:7], v6 offset0:12 offset1:142
	ds_read2_b32 v[8:9], v8 offset0:77 offset1:207
	s_waitcnt lgkmcnt(0)
	v_cvt_pk_bf16_f32 v6, v6, v8
	v_add_u32_e32 v8, s16, v11
	v_cvt_pk_bf16_f32 v7, v7, v9
	v_ashrrev_i32_e32 v9, 31, v8
	v_lshlrev_b64 v[8:9], 9, v[8:9]
	v_lshl_add_u64 v[8:9], s[0:1], 0, v[8:9]
	v_lshl_add_u64 v[8:9], v[8:9], 0, s[20:21]
	v_mov_b32_e32 v11, v96
	v_lshl_add_u64 v[8:9], v[8:9], 0, v[10:11]
	global_store_dwordx4 v[8:9], v[0:3], off
	global_store_dwordx4 v[8:9], v[4:7], off offset:16
	s_barrier

; DI void conv_tile(const float* __restrict__ src, int N, u16* __restrict__ dst, int ldd, int k0, int n0, int mode,
;                   const float* __restrict__ kscale, float* tl) {
;   const int t = get_tid();
;   const int r = t >> 4, c4 = (t & 15) * 4;
; #pragma unroll
;   for (int i = 0; i < 4; ++i) {
;     const int k = r + 16 * i;
;     float4 v = make_float4(0.f, 0.f, 0.f, 0.f);
;     if (n0 + c4 < N) v = *(const float4*)(src + (size_t)(k0 + k) * N + n0 + c4);
;     if (kscale) { const float s = kscale[k0 + k]; v.x *= s; v.y *= s; v.z *= s; v.w *= s; }
;     float* q = tl + k * 65 + c4;
;     q[0] = v.x; q[1] = v.y; q[2] = v.z; q[3] = v.w;
;   }
;   __syncthreads();
;   const int n = t >> 2, ks = (t & 3) * 16;
;   unsigned w[8];
; #pragma unroll
;   for (int j = 0; j < 8; ++j) w[j] = pack2(tl[(ks + 2 * j) * 65 + n], tl[(ks + 2 * j + 1) * 65 + n]);
;   const int nn = n0 + n;
;   const int drow = mode == 0 ? nn : ((nn >> 5) * 64 + (nn & 31) + (mode == 2 ? 32 : 0));
;   uint4* d = (uint4*)(dst + (size_t)drow * ldd + k0 + ks);
;   d[0] = make_uint4(w[0], w[1], w[2], w[3]);
;   d[1] = make_uint4(w[4], w[5], w[6], w[7]);
;   __syncthreads();
; }
; DI void convert_weights(const P& p, int layer, char* smem, int vb, int nvb, int part) {
;     ...
;       } else {
;         const float* src = p.ffn_d + woff;
;         u16* dst = (u16*)(ws + OFF_WDN) + (size_t)s * 1024 * 2816;
;         conv_tile(src, 1024, dst, 2816, (jj / 16) * 64, (jj % 16) * 64, 0, nullptr, tl);
.LBB0_1150:
	s_andn2_b64 vcc, exec, s[0:1]
	s_cbranch_vccnz .LBB0_1111
	s_mul_hi_i32 s0, s15, 0x3e0f83e1
	s_lshr_b32 s1, s0, 31
	s_ashr_i32 s17, s0, 9
	s_add_i32 s17, s17, s1
	s_mul_i32 s0, s17, 0x840
	s_sub_i32 s18, s15, s0
	s_mul_i32 s0, s18, 0xba3
	s_lshr_b32 s1, s0, 31
	s_ashr_i32 s15, s0, 21
	s_add_i32 s15, s15, s1
	s_mul_i32 s0, s15, 0x2c0
	s_sub_i32 s16, s18, s0
	s_mul_hi_i32 s1, s17, 0x2c0000
	s_mul_i32 s0, s17, 0x2c0000
	s_mov_b64 s[4:5], -1
	s_cmpk_gt_i32 s18, 0x57f
	s_sext_i32_i16 s19, s16
	s_cbranch_scc0 .LBB0_1153
	v_readlane_b32 s76, v223, 6
	s_lshl_b64 s[4:5], s[0:1], 2
	v_readlane_b32 s78, v223, 8
	v_readlane_b32 s79, v223, 9
	s_add_u32 s20, s78, s4
	s_addc_u32 s39, s79, s5
	s_mul_i32 s4, s17, 0x580000
	v_readlane_b32 s42, v221, 10
	s_mul_hi_i32 s5, s17, 0x580000
	v_readlane_b32 s43, v221, 11
	s_add_u32 s4, s42, s4
	s_addc_u32 s5, s43, s5
	s_lshl_b32 s38, s19, 2
	s_and_b32 s41, s38, 0xfc0
	s_lshl_b32 s38, s19, 6
	s_and_b32 s42, s38, 0x3c0
	v_mov_b32_e32 v8, v132
	s_lshl_b32 s38, s42, 2
	v_ashrrev_i32_e32 v9, 4, v8
	v_lshlrev_b32_e32 v10, 4, v8
	s_add_u32 s38, s20, s38
	v_add_u32_e32 v6, s41, v9
	v_and_b32_e32 v0, 0xf0, v10
	s_addc_u32 s39, s39, 0
	v_mov_b32_e32 v1, v96
	v_ashrrev_i32_e32 v7, 31, v6
	v_lshl_add_u64 v[4:5], s[38:39], 0, v[0:1]
	v_lshlrev_b64 v[2:3], 12, v[6:7]
	s_movk_i32 s20, 0x104
	v_lshl_add_u64 v[2:3], v[4:5], 0, v[2:3]
	v_mul_lo_u32 v1, v9, s20
	v_add3_u32 v7, 0, v0, v1
	global_load_dwordx4 v[0:3], v[2:3], off
	v_add_u32_e32 v236, 16, v6
	v_ashrrev_i32_e32 v237, 31, v236
	v_lshlrev_b64 v[236:237], 12, v[236:237]
	v_lshl_add_u64 v[236:237], v[4:5], 0, v[236:237]
	global_load_dwordx4 v[224:227], v[236:237], off
	v_add_u32_e32 v236, 32, v6
	v_ashrrev_i32_e32 v237, 31, v236
	v_lshlrev_b64 v[236:237], 12, v[236:237]
	v_lshl_add_u64 v[236:237], v[4:5], 0, v[236:237]
	global_load_dwordx4 v[228:231], v[236:237], off
	v_add_u32_e32 v236, 48, v6
	v_ashrrev_i32_e32 v237, 31, v236
	v_lshlrev_b64 v[236:237], 12, v[236:237]
	v_lshl_add_u64 v[236:237], v[4:5], 0, v[236:237]
	global_load_dwordx4 v[232:235], v[236:237], off
	v_add_u32_e32 v9, 0x1040, v7
	v_and_b32_e32 v10, 48, v10
	v_ashrrev_i32_e32 v11, 2, v8
	v_add_u32_e32 v11, s42, v11
	s_lshl_b32 s20, s41, 1
	v_readlane_b32 s77, v223, 7
	v_readlane_b32 s80, v223, 10
	v_readlane_b32 s81, v223, 11
	v_readlane_b32 s82, v223, 12
	v_readlane_b32 s83, v223, 13
	v_readlane_b32 s84, v223, 14
	v_readlane_b32 s85, v223, 15
	v_readlane_b32 s86, v223, 16
	v_readlane_b32 s87, v223, 17
	v_readlane_b32 s88, v223, 18
	v_readlane_b32 s89, v223, 19
	v_readlane_b32 s90, v223, 20
	v_readlane_b32 s91, v223, 21
	s_waitcnt vmcnt(3)
	ds_write2_b32 v7, v0, v1 offset1:1
	ds_write2_b32 v7, v2, v3 offset0:2 offset1:3
	s_waitcnt vmcnt(2)
	ds_write2_b32 v9, v224, v225 offset1:1
	v_add_u32_e32 v0, 0x1048, v7
	ds_write2_b32 v0, v226, v227 offset1:1
	v_add_u32_e32 v9, 0x2080, v7
	s_waitcnt vmcnt(1)
	ds_write2_b32 v9, v228, v229 offset1:1
	v_add_u32_e32 v0, 0x2088, v7
	ds_write2_b32 v0, v230, v231 offset1:1
	v_add_u32_e32 v4, 0x30c0, v7
	s_waitcnt vmcnt(0)
	ds_write2_b32 v4, v232, v233 offset1:1
	v_add_u32_e32 v0, 0x30c8, v7
	ds_write2_b32 v0, v234, v235 offset1:1
	v_mul_u32_u24_e32 v0, 0x41, v10
	v_and_b32_e32 v2, -4, v8
	v_lshlrev_b32_e32 v3, 2, v0
	v_add3_u32 v8, 0, v2, v3
	v_add3_u32 v9, 0, v3, v2
	s_waitcnt lgkmcnt(0)
	s_barrier
	ds_read2_b32 v[0:1], v8 offset1:130
	ds_read2_b32 v[2:3], v9 offset0:65 offset1:195
	v_add_u32_e32 v4, 0x400, v9
	ds_read2_b32 v[4:5], v4 offset0:69 offset1:199
	v_add_u32_e32 v6, 0x800, v9
	ds_read2_b32 v[6:7], v6 offset0:73 offset1:203
	s_waitcnt lgkmcnt(2)
	v_cvt_pk_bf16_f32 v0, v0, v2
	v_add_u32_e32 v2, 0x400, v8
	v_cvt_pk_bf16_f32 v1, v1, v3
	ds_read2_b32 v[2:3], v2 offset0:4 offset1:134
	v_lshlrev_b32_e32 v10, 1, v10
	s_waitcnt lgkmcnt(0)
	v_cvt_pk_bf16_f32 v2, v2, v4
	v_add_u32_e32 v4, 0x800, v8
	v_cvt_pk_bf16_f32 v3, v3, v5
	ds_read2_b32 v[4:5], v4 offset0:8 offset1:138
	s_waitcnt lgkmcnt(0)
	v_cvt_pk_bf16_f32 v4, v4, v6
	v_add_u32_e32 v6, 0xc00, v8
	v_add_u32_e32 v8, 0xc00, v9
	v_cvt_pk_bf16_f32 v5, v5, v7
	ds_read2_b32 v[6:7], v6 offset0:12 offset1:142
	ds_read2_b32 v[8:9], v8 offset0:77 offset1:207
	s_waitcnt lgkmcnt(0)
	v_cvt_pk_bf16_f32 v6, v6, v8
	v_cvt_pk_bf16_f32 v7, v7, v9
	v_mov_b64_e32 v[8:9], s[4:5]
	s_movk_i32 s4, 0x1600
	v_mad_i64_i32 v[8:9], s[4:5], v11, s4, v[8:9]
	v_lshl_add_u64 v[8:9], v[8:9], 0, s[20:21]
	v_mov_b32_e32 v11, v96
	v_lshl_add_u64 v[8:9], v[8:9], 0, v[10:11]
	global_store_dwordx4 v[8:9], v[0:3], off
	global_store_dwordx4 v[8:9], v[4:7], off offset:16
	s_barrier
	s_mov_b64 s[4:5], 0
; DI void conv_tile(const float* __restrict__ src, int N, u16* __restrict__ dst, int ldd, int k0, int n0, int mode,
;                   const float* __restrict__ kscale, float* tl) {
;   const int t = get_tid();
;   const int r = t >> 4, c4 = (t & 15) * 4;
; #pragma unroll
;   for (int i = 0; i < 4; ++i) {
;     const int k = r + 16 * i;
;     float4 v = make_float4(0.f, 0.f, 0.f, 0.f);
;     if (n0 + c4 < N) v = *(const float4*)(src + (size_t)(k0 + k) * N + n0 + c4);
;     if (kscale) { const float s = kscale[k0 + k]; v.x *= s; v.y *= s; v.z *= s; v.w *= s; }
;     float* q = tl + k * 65 + c4;
;     q[0] = v.x; q[1] = v.y; q[2] = v.z; q[3] = v.w;
;   }
;   __syncthreads();
;   const int n = t >> 2, ks = (t & 3) * 16;
;   unsigned w[8];
; #pragma unroll
;   for (int j = 0; j < 8; ++j) w[j] = pack2(tl[(ks + 2 * j) * 65 + n], tl[(ks + 2 * j + 1) * 65 + n]);
;   const int nn = n0 + n;
;   const int drow = mode == 0 ? nn : ((nn >> 5) * 64 + (nn & 31) + (mode == 2 ? 32 : 0));
;   uint4* d = (uint4*)(dst + (size_t)drow * ldd + k0 + ks);
;   d[0] = make_uint4(w[0], w[1], w[2], w[3]);
;   d[1] = make_uint4(w[4], w[5], w[6], w[7]);
;   __syncthreads();
; }
; DI void convert_weights(const P& p, int layer, char* smem, int vb, int nvb, int part) {
;     ...
;       if (which < 2) {
;         const float* src = (which == 0 ? p.ffn_g : p.ffn_u) + woff;
;         u16* dst = (u16*)(ws + OFF_WGU) + (size_t)s * 5632 * 1024;
;         conv_tile(src, 2816, dst, 1024, (jj / 44) * 64, (jj % 44) * 64, 1 + which, nullptr, tl);
.LBB0_1153:
	s_andn2_b64 vcc, exec, s[4:5]
	s_cbranch_vccnz .LBB0_1111
	v_readlane_b32 s76, v223, 22
	v_readlane_b32 s77, v223, 23
	v_readlane_b32 s78, v223, 24
	v_readlane_b32 s79, v223, 25
	v_readlane_b32 s80, v223, 26
	v_readlane_b32 s81, v223, 27
	v_readlane_b32 s82, v223, 28
	v_readlane_b32 s83, v223, 29
	v_readlane_b32 s84, v223, 30
	v_readlane_b32 s85, v223, 31
	v_readlane_b32 s86, v223, 32
	v_readlane_b32 s87, v223, 33
	s_addk_i32 s18, 0x2bf
	v_readlane_b32 s72, v223, 6
	s_cmpk_lt_u32 s18, 0x57f
	v_readlane_b32 s90, v223, 36
	v_readlane_b32 s91, v223, 37
	v_readlane_b32 s73, v223, 7
	s_cselect_b32 s4, s91, s73
	s_cselect_b32 s5, s90, s72
	s_lshl_b64 s[0:1], s[0:1], 2
	s_add_u32 s18, s5, s0
	s_addc_u32 s20, s4, s1
	s_mul_hi_i32 s1, s17, 0xb00000
	s_mul_i32 s17, s17, 0xb00000
	s_add_u32 s0, s70, s17
	s_mulk_i32 s19, 0xba3
	s_addc_u32 s1, s71, s1
	s_lshr_b32 s4, s19, 31
	s_ashr_i32 s5, s19, 17
	s_add_i32 s5, s5, s4
	s_sext_i32_i16 s4, s5
	s_mul_i32 s5, s5, 44
	s_sub_i32 s5, s16, s5
	s_sext_i32_i16 s5, s5
	s_add_i32 s15, s15, 1
	s_lshl_b32 s4, s4, 6
	s_lshl_b32 s38, s5, 6
	s_and_b32 s5, s15, 0xffff
	s_cmp_eq_u32 s5, 0
	s_cselect_b64 vcc, -1, 0
	s_ashr_i32 s39, s38, 31
	v_mov_b32_e32 v6, v132
	s_lshl_b64 s[16:17], s[38:39], 2
	s_add_u32 s16, s18, s16
	v_lshlrev_b32_e32 v8, 4, v6
	v_ashrrev_i32_e32 v7, 4, v6
	v_and_b32_e32 v0, 0xf0, v8
	s_addc_u32 s17, s20, s17
	v_mov_b32_e32 v1, v96
	v_lshl_add_u64 v[4:5], s[16:17], 0, v[0:1]
	v_add_u32_e32 v9, s4, v7
	s_movk_i32 s15, 0x2c00
	v_mad_i64_i32 v[2:3], s[16:17], v9, s15, v[4:5]
	s_movk_i32 s16, 0x104
	s_nop 0
	v_mul_lo_u32 v1, v7, s16
	v_add3_u32 v7, 0, v0, v1
	global_load_dwordx4 v[0:3], v[2:3], off
	v_add_u32_e32 v236, 16, v9
	v_mad_i64_i32 v[236:237], s[16:17], v236, s15, v[4:5]
	global_load_dwordx4 v[224:227], v[236:237], off
	v_add_u32_e32 v236, 32, v9
	v_mad_i64_i32 v[236:237], s[16:17], v236, s15, v[4:5]
	global_load_dwordx4 v[228:231], v[236:237], off
	v_add_u32_e32 v236, 48, v9
	v_mad_i64_i32 v[236:237], s[16:17], v236, s15, v[4:5]
	global_load_dwordx4 v[232:235], v[236:237], off
	v_add_u32_e32 v10, 0x1040, v7
	v_and_b32_e32 v11, 48, v8
	s_cmp_eq_u32 s5, 2
	s_cselect_b32 s5, 32, 0
	v_readlane_b32 s88, v223, 34
	v_readlane_b32 s89, v223, 35
	v_readlane_b32 s74, v223, 8
	v_readlane_b32 s75, v223, 9
	v_readlane_b32 s76, v223, 10
	v_readlane_b32 s77, v223, 11
	v_readlane_b32 s78, v223, 12
	v_readlane_b32 s79, v223, 13
	v_readlane_b32 s80, v223, 14
	v_readlane_b32 s81, v223, 15
	v_readlane_b32 s82, v223, 16
	v_readlane_b32 s83, v223, 17
	v_readlane_b32 s84, v223, 18
	v_readlane_b32 s85, v223, 19
	v_readlane_b32 s86, v223, 20
	v_readlane_b32 s87, v223, 21
	s_waitcnt vmcnt(3)
	ds_write2_b32 v7, v0, v1 offset1:1
	ds_write2_b32 v7, v2, v3 offset0:2 offset1:3
	s_waitcnt vmcnt(2)
	ds_write2_b32 v10, v224, v225 offset1:1
	v_add_u32_e32 v0, 0x1048, v7
	ds_write2_b32 v0, v226, v227 offset1:1
	v_add_u32_e32 v10, 0x2080, v7
	s_waitcnt vmcnt(1)
	ds_write2_b32 v10, v228, v229 offset1:1
	v_add_u32_e32 v0, 0x2088, v7
	ds_write2_b32 v0, v230, v231 offset1:1
	v_add_u32_e32 v4, 0x30c0, v7
	v_ashrrev_i32_e32 v10, 2, v6
	s_waitcnt vmcnt(0)
	ds_write2_b32 v4, v232, v233 offset1:1
	v_add_u32_e32 v0, 0x30c8, v7
	ds_write2_b32 v0, v234, v235 offset1:1
	v_mul_u32_u24_e32 v0, 0x41, v11
	v_and_b32_e32 v2, -4, v6
	v_lshlrev_b32_e32 v3, 2, v0
	v_add3_u32 v8, 0, v2, v3
	v_add3_u32 v9, 0, v3, v2
	s_waitcnt lgkmcnt(0)
	s_barrier
	ds_read2_b32 v[0:1], v8 offset1:130
	ds_read2_b32 v[2:3], v9 offset0:65 offset1:195
	v_add_u32_e32 v4, 0x400, v9
	ds_read2_b32 v[4:5], v4 offset0:69 offset1:199
	v_add_u32_e32 v6, 0x800, v9
	ds_read2_b32 v[6:7], v6 offset0:73 offset1:203
	s_waitcnt lgkmcnt(2)
	v_cvt_pk_bf16_f32 v0, v0, v2
	v_add_u32_e32 v2, 0x400, v8
	v_cvt_pk_bf16_f32 v1, v1, v3
	ds_read2_b32 v[2:3], v2 offset0:4 offset1:134
	s_waitcnt lgkmcnt(0)
	v_cvt_pk_bf16_f32 v2, v2, v4
	v_add_u32_e32 v4, 0x800, v8
	v_cvt_pk_bf16_f32 v3, v3, v5
	ds_read2_b32 v[4:5], v4 offset0:8 offset1:138
	s_waitcnt lgkmcnt(0)
	v_cvt_pk_bf16_f32 v4, v4, v6
	v_add_u32_e32 v6, 0xc00, v8
	v_add_u32_e32 v8, 0xc00, v9
	v_cvt_pk_bf16_f32 v5, v5, v7
	ds_read2_b32 v[6:7], v6 offset0:12 offset1:142
	ds_read2_b32 v[8:9], v8 offset0:77 offset1:207
	s_waitcnt lgkmcnt(0)
	v_cvt_pk_bf16_f32 v6, v6, v8
	v_add_u32_e32 v8, s38, v10
	v_cvt_pk_bf16_f32 v7, v7, v9
	v_lshlrev_b32_e32 v9, 1, v8
	v_and_b32_e32 v9, 0xffffffc0, v9
	v_and_b32_e32 v10, 31, v10
	v_or3_b32 v9, v10, s5, v9
	v_cndmask_b32_e32 v8, v9, v8, vcc
	v_ashrrev_i32_e32 v9, 31, v8
	v_lshlrev_b64 v[8:9], 11, v[8:9]
	v_lshl_add_u64 v[8:9], s[0:1], 0, v[8:9]
	s_ashr_i32 s5, s4, 31
	v_lshl_add_u64 v[8:9], s[4:5], 1, v[8:9]
	v_lshlrev_b32_e32 v10, 1, v11
	v_mov_b32_e32 v11, v96
	v_lshl_add_u64 v[8:9], v[8:9], 0, v[10:11]
	global_store_dwordx4 v[8:9], v[0:3], off
	global_store_dwordx4 v[8:9], v[4:7], off offset:16
	s_barrier
	s_branch .LBB0_1111

; DI void conv_tile(const float* __restrict__ src, int N, u16* __restrict__ dst, int ldd, int k0, int n0, int mode,
;                   const float* __restrict__ kscale, float* tl) {
;   const int t = get_tid();
;   const int r = t >> 4, c4 = (t & 15) * 4;
; #pragma unroll
;   for (int i = 0; i < 4; ++i) {
;     const int k = r + 16 * i;
;     float4 v = make_float4(0.f, 0.f, 0.f, 0.f);
;     if (n0 + c4 < N) v = *(const float4*)(src + (size_t)(k0 + k) * N + n0 + c4);
;     if (kscale) { const float s = kscale[k0 + k]; v.x *= s; v.y *= s; v.z *= s; v.w *= s; }
;     float* q = tl + k * 65 + c4;
;     q[0] = v.x; q[1] = v.y; q[2] = v.z; q[3] = v.w;
;   }
;   __syncthreads();
;   const int n = t >> 2, ks = (t & 3) * 16;
;   unsigned w[8];
; #pragma unroll
;   for (int j = 0; j < 8; ++j) w[j] = pack2(tl[(ks + 2 * j) * 65 + n], tl[(ks + 2 * j + 1) * 65 + n]);
;   const int nn = n0 + n;
;   const int drow = mode == 0 ? nn : ((nn >> 5) * 64 + (nn & 31) + (mode == 2 ? 32 : 0));
;   uint4* d = (uint4*)(dst + (size_t)drow * ldd + k0 + ks);
;   d[0] = make_uint4(w[0], w[1], w[2], w[3]);
;   d[1] = make_uint4(w[4], w[5], w[6], w[7]);
;   __syncthreads();
; }
; DI void convert_weights(const P& p, int layer, char* smem, int vb, int nvb, int part) {
;     ...
;       } else {
;         const float* src = p.ffn_d + woff;
;         u16* dst = (u16*)(ws + OFF_WDN) + (size_t)s * 1024 * 2816;
;         conv_tile(src, 1024, dst, 2816, (jj / 16) * 64, (jj % 16) * 64, 0, nullptr, tl);
.LBB0_1166:
	s_and_b64 vcc, exec, s[0:1]
	s_cbranch_vccz .LBB0_1155
	s_mul_hi_i32 s0, s4, 0x3e0f83e1
	s_lshr_b32 s1, s0, 31
	s_ashr_i32 s18, s0, 9
	s_add_i32 s18, s18, s1
	s_mul_i32 s0, s18, 0x840
	s_sub_i32 s19, s4, s0
	s_mul_i32 s0, s19, 0xba3
	s_lshr_b32 s1, s0, 31
	s_ashr_i32 s16, s0, 21
	s_add_i32 s16, s16, s1
	s_mul_i32 s0, s16, 0x2c0
	s_sub_i32 s17, s19, s0
	s_mul_i32 s0, s18, 0x2c0000
	s_mul_hi_i32 s1, s18, 0x2c0000
	s_add_u32 s0, s0, 0x580000
	s_addc_u32 s1, s1, 0
	s_mov_b64 s[4:5], -1
	s_cmpk_gt_i32 s19, 0x57f
	s_sext_i32_i16 s38, s17
	s_cbranch_scc0 .LBB0_1169
	v_readlane_b32 s76, v223, 6
	s_lshl_b64 s[4:5], s[0:1], 2
	v_readlane_b32 s78, v223, 8
	v_readlane_b32 s79, v223, 9
	s_add_u32 s20, s78, s4
	s_addc_u32 s39, s79, s5
	s_mul_i32 s4, s18, 0x580000
	v_readlane_b32 s40, v221, 10
	s_mul_hi_i32 s5, s18, 0x580000
	v_readlane_b32 s41, v221, 11
	s_add_u32 s4, s40, s4
	s_addc_u32 s5, s41, s5
	s_lshl_b32 s40, s38, 2
	s_and_b32 s42, s40, 0xfc0
	s_lshl_b32 s40, s38, 6
	s_and_b32 s43, s40, 0x3c0
	v_mov_b32_e32 v8, v132
	s_lshl_b32 s40, s43, 2
	v_ashrrev_i32_e32 v9, 4, v8
	v_lshlrev_b32_e32 v10, 4, v8
	s_add_u32 s40, s20, s40
	v_add_u32_e32 v6, s42, v9
	v_and_b32_e32 v0, 0xf0, v10
	s_addc_u32 s41, s39, 0
	v_mov_b32_e32 v1, v96
	v_ashrrev_i32_e32 v7, 31, v6
	v_lshl_add_u64 v[4:5], s[40:41], 0, v[0:1]
	v_lshlrev_b64 v[2:3], 12, v[6:7]
	s_movk_i32 s20, 0x104
	v_lshl_add_u64 v[2:3], v[4:5], 0, v[2:3]
	v_mul_lo_u32 v1, v9, s20
	v_add3_u32 v7, 0, v0, v1
	global_load_dwordx4 v[0:3], v[2:3], off
	v_add_u32_e32 v236, 16, v6
	v_ashrrev_i32_e32 v237, 31, v236
	v_lshlrev_b64 v[236:237], 12, v[236:237]
	v_lshl_add_u64 v[236:237], v[4:5], 0, v[236:237]
	global_load_dwordx4 v[224:227], v[236:237], off
	v_add_u32_e32 v236, 32, v6
	v_ashrrev_i32_e32 v237, 31, v236
	v_lshlrev_b64 v[236:237], 12, v[236:237]
	v_lshl_add_u64 v[236:237], v[4:5], 0, v[236:237]
	global_load_dwordx4 v[228:231], v[236:237], off
	v_add_u32_e32 v236, 48, v6
	v_ashrrev_i32_e32 v237, 31, v236
	v_lshlrev_b64 v[236:237], 12, v[236:237]
	v_lshl_add_u64 v[236:237], v[4:5], 0, v[236:237]
	global_load_dwordx4 v[232:235], v[236:237], off
	v_add_u32_e32 v9, 0x1040, v7
	v_and_b32_e32 v10, 48, v10
	v_ashrrev_i32_e32 v11, 2, v8
	v_add_u32_e32 v11, s43, v11
	s_lshl_b32 s20, s42, 1
	v_readlane_b32 s77, v223, 7
	v_readlane_b32 s80, v223, 10
	v_readlane_b32 s81, v223, 11
	v_readlane_b32 s82, v223, 12
	v_readlane_b32 s83, v223, 13
	v_readlane_b32 s84, v223, 14
	v_readlane_b32 s85, v223, 15
	v_readlane_b32 s86, v223, 16
	v_readlane_b32 s87, v223, 17
	v_readlane_b32 s88, v223, 18
	v_readlane_b32 s89, v223, 19
	v_readlane_b32 s90, v223, 20
	v_readlane_b32 s91, v223, 21
	s_waitcnt vmcnt(3)
	ds_write2_b32 v7, v0, v1 offset1:1
	ds_write2_b32 v7, v2, v3 offset0:2 offset1:3
	s_waitcnt vmcnt(2)
	ds_write2_b32 v9, v224, v225 offset1:1
	v_add_u32_e32 v0, 0x1048, v7
	ds_write2_b32 v0, v226, v227 offset1:1
	v_add_u32_e32 v9, 0x2080, v7
	s_waitcnt vmcnt(1)
	ds_write2_b32 v9, v228, v229 offset1:1
	v_add_u32_e32 v0, 0x2088, v7
	ds_write2_b32 v0, v230, v231 offset1:1
	v_add_u32_e32 v4, 0x30c0, v7
	s_waitcnt vmcnt(0)
	ds_write2_b32 v4, v232, v233 offset1:1
	v_add_u32_e32 v0, 0x30c8, v7
	ds_write2_b32 v0, v234, v235 offset1:1
	v_mul_u32_u24_e32 v0, 0x41, v10
	v_and_b32_e32 v2, -4, v8
	v_lshlrev_b32_e32 v3, 2, v0
	v_add3_u32 v8, 0, v2, v3
	v_add3_u32 v9, 0, v3, v2
	s_waitcnt lgkmcnt(0)
	s_barrier
	ds_read2_b32 v[0:1], v8 offset1:130
	ds_read2_b32 v[2:3], v9 offset0:65 offset1:195
	v_add_u32_e32 v4, 0x400, v9
	ds_read2_b32 v[4:5], v4 offset0:69 offset1:199
	v_add_u32_e32 v6, 0x800, v9
	ds_read2_b32 v[6:7], v6 offset0:73 offset1:203
	s_waitcnt lgkmcnt(2)
	v_cvt_pk_bf16_f32 v0, v0, v2
	v_add_u32_e32 v2, 0x400, v8
	v_cvt_pk_bf16_f32 v1, v1, v3
	ds_read2_b32 v[2:3], v2 offset0:4 offset1:134
	v_lshlrev_b32_e32 v10, 1, v10
	s_waitcnt lgkmcnt(0)
	v_cvt_pk_bf16_f32 v2, v2, v4
	v_add_u32_e32 v4, 0x800, v8
	v_cvt_pk_bf16_f32 v3, v3, v5
	ds_read2_b32 v[4:5], v4 offset0:8 offset1:138
	s_waitcnt lgkmcnt(0)
	v_cvt_pk_bf16_f32 v4, v4, v6
	v_add_u32_e32 v6, 0xc00, v8
	v_add_u32_e32 v8, 0xc00, v9
	v_cvt_pk_bf16_f32 v5, v5, v7
	ds_read2_b32 v[6:7], v6 offset0:12 offset1:142
	ds_read2_b32 v[8:9], v8 offset0:77 offset1:207
	s_waitcnt lgkmcnt(0)
	v_cvt_pk_bf16_f32 v6, v6, v8
	v_cvt_pk_bf16_f32 v7, v7, v9
	v_mov_b64_e32 v[8:9], s[4:5]
	s_movk_i32 s4, 0x1600
	v_mad_i64_i32 v[8:9], s[4:5], v11, s4, v[8:9]
	v_lshl_add_u64 v[8:9], v[8:9], 0, s[20:21]
	v_mov_b32_e32 v11, v96
	v_lshl_add_u64 v[8:9], v[8:9], 0, v[10:11]
	global_store_dwordx4 v[8:9], v[0:3], off
	global_store_dwordx4 v[8:9], v[4:7], off offset:16
	s_barrier
	s_mov_b64 s[4:5], 0
; DI void conv_tile(const float* __restrict__ src, int N, u16* __restrict__ dst, int ldd, int k0, int n0, int mode,
;                   const float* __restrict__ kscale, float* tl) {
;   const int t = get_tid();
;   const int r = t >> 4, c4 = (t & 15) * 4;
; #pragma unroll
;   for (int i = 0; i < 4; ++i) {
;     const int k = r + 16 * i;
;     float4 v = make_float4(0.f, 0.f, 0.f, 0.f);
;     if (n0 + c4 < N) v = *(const float4*)(src + (size_t)(k0 + k) * N + n0 + c4);
;     if (kscale) { const float s = kscale[k0 + k]; v.x *= s; v.y *= s; v.z *= s; v.w *= s; }
;     float* q = tl + k * 65 + c4;
;     q[0] = v.x; q[1] = v.y; q[2] = v.z; q[3] = v.w;
;   }
;   __syncthreads();
;   const int n = t >> 2, ks = (t & 3) * 16;
;   unsigned w[8];
; #pragma unroll
;   for (int j = 0; j < 8; ++j) w[j] = pack2(tl[(ks + 2 * j) * 65 + n], tl[(ks + 2 * j + 1) * 65 + n]);
;   const int nn = n0 + n;
;   const int drow = mode == 0 ? nn : ((nn >> 5) * 64 + (nn & 31) + (mode == 2 ? 32 : 0));
;   uint4* d = (uint4*)(dst + (size_t)drow * ldd + k0 + ks);
;   d[0] = make_uint4(w[0], w[1], w[2], w[3]);
;   d[1] = make_uint4(w[4], w[5], w[6], w[7]);
;   __syncthreads();
; }
; DI void convert_weights(const P& p, int layer, char* smem, int vb, int nvb, int part) {
;     ...
;       if (which < 2) {
;         const float* src = (which == 0 ? p.ffn_g : p.ffn_u) + woff;
;         u16* dst = (u16*)(ws + OFF_WGU) + (size_t)s * 5632 * 1024;
;         conv_tile(src, 2816, dst, 1024, (jj / 44) * 64, (jj % 44) * 64, 1 + which, nullptr, tl);
.LBB0_1169:
	s_andn2_b64 vcc, exec, s[4:5]
	s_cbranch_vccnz .LBB0_1155
	v_readlane_b32 s76, v223, 22
	v_readlane_b32 s77, v223, 23
	v_readlane_b32 s78, v223, 24
	v_readlane_b32 s79, v223, 25
	v_readlane_b32 s80, v223, 26
	v_readlane_b32 s81, v223, 27
	v_readlane_b32 s82, v223, 28
	v_readlane_b32 s83, v223, 29
	v_readlane_b32 s84, v223, 30
	v_readlane_b32 s85, v223, 31
	v_readlane_b32 s86, v223, 32
	v_readlane_b32 s87, v223, 33
	v_readlane_b32 s88, v223, 34
	v_readlane_b32 s89, v223, 35
	s_addk_i32 s19, 0x2bf
	v_readlane_b32 s90, v223, 36
	v_readlane_b32 s91, v223, 37
	s_mov_b64 s[52:53], s[88:89]
	v_readlane_b32 s72, v223, 6
	s_cmpk_lt_u32 s19, 0x57f
	s_mov_b64 s[54:55], s[90:91]
	v_readlane_b32 s73, v223, 7
	s_cselect_b32 s4, s55, s73
	s_cselect_b32 s5, s54, s72
	s_lshl_b64 s[0:1], s[0:1], 2
	s_add_u32 s19, s5, s0
	s_addc_u32 s20, s4, s1
	s_mul_hi_i32 s1, s18, 0xb00000
	s_mul_i32 s18, s18, 0xb00000
	s_add_u32 s0, s70, s18
	s_mulk_i32 s38, 0xba3
	s_addc_u32 s1, s71, s1
	s_lshr_b32 s4, s38, 31
	s_ashr_i32 s5, s38, 17
	s_add_i32 s5, s5, s4
	s_sext_i32_i16 s4, s5
	s_mul_i32 s5, s5, 44
	s_sub_i32 s5, s17, s5
	s_sext_i32_i16 s5, s5
	s_add_i32 s16, s16, 1
	s_lshl_b32 s4, s4, 6
	s_lshl_b32 s38, s5, 6
	s_and_b32 s5, s16, 0xffff
	s_cmp_eq_u32 s5, 0
	s_cselect_b64 vcc, -1, 0
	s_ashr_i32 s39, s38, 31
	v_mov_b32_e32 v6, v132
	s_lshl_b64 s[16:17], s[38:39], 2
	s_add_u32 s16, s19, s16
	v_lshlrev_b32_e32 v8, 4, v6
	v_ashrrev_i32_e32 v7, 4, v6
	v_and_b32_e32 v0, 0xf0, v8
	s_addc_u32 s17, s20, s17
	v_mov_b32_e32 v1, v96
	v_lshl_add_u64 v[4:5], s[16:17], 0, v[0:1]
	v_add_u32_e32 v9, s4, v7
	s_movk_i32 s18, 0x2c00
	v_mad_i64_i32 v[2:3], s[16:17], v9, s18, v[4:5]
	s_movk_i32 s16, 0x104
	s_nop 0
	v_mul_lo_u32 v1, v7, s16
	v_add3_u32 v7, 0, v0, v1
	global_load_dwordx4 v[0:3], v[2:3], off
	v_add_u32_e32 v236, 16, v9
	v_mad_i64_i32 v[236:237], s[16:17], v236, s18, v[4:5]
	global_load_dwordx4 v[224:227], v[236:237], off
	v_add_u32_e32 v236, 32, v9
	v_mad_i64_i32 v[236:237], s[16:17], v236, s18, v[4:5]
	global_load_dwordx4 v[228:231], v[236:237], off
	v_add_u32_e32 v236, 48, v9
	v_mad_i64_i32 v[236:237], s[16:17], v236, s18, v[4:5]
	global_load_dwordx4 v[232:235], v[236:237], off
	v_add_u32_e32 v10, 0x1040, v7
	v_and_b32_e32 v11, 48, v8
	s_cmp_eq_u32 s5, 2
	s_cselect_b32 s5, 32, 0
	v_readlane_b32 s74, v223, 8
	v_readlane_b32 s75, v223, 9
	v_readlane_b32 s76, v223, 10
	v_readlane_b32 s77, v223, 11
	v_readlane_b32 s78, v223, 12
	v_readlane_b32 s79, v223, 13
	v_readlane_b32 s80, v223, 14
	v_readlane_b32 s81, v223, 15
	v_readlane_b32 s82, v223, 16
	v_readlane_b32 s83, v223, 17
	v_readlane_b32 s84, v223, 18
	v_readlane_b32 s85, v223, 19
	v_readlane_b32 s86, v223, 20
	v_readlane_b32 s87, v223, 21
	v_readlane_b32 s54, v218, 44
	s_waitcnt vmcnt(3)
	ds_write2_b32 v7, v0, v1 offset1:1
	ds_write2_b32 v7, v2, v3 offset0:2 offset1:3
	s_waitcnt vmcnt(2)
	ds_write2_b32 v10, v224, v225 offset1:1
	v_add_u32_e32 v0, 0x1048, v7
	ds_write2_b32 v0, v226, v227 offset1:1
	v_add_u32_e32 v10, 0x2080, v7
	s_waitcnt vmcnt(1)
	ds_write2_b32 v10, v228, v229 offset1:1
	v_add_u32_e32 v0, 0x2088, v7
	ds_write2_b32 v0, v230, v231 offset1:1
	v_add_u32_e32 v4, 0x30c0, v7
	v_ashrrev_i32_e32 v10, 2, v6
	s_waitcnt vmcnt(0)
	ds_write2_b32 v4, v232, v233 offset1:1
	v_add_u32_e32 v0, 0x30c8, v7
	ds_write2_b32 v0, v234, v235 offset1:1
	v_mul_u32_u24_e32 v0, 0x41, v11
	v_and_b32_e32 v2, -4, v6
	v_lshlrev_b32_e32 v3, 2, v0
	v_add3_u32 v8, 0, v2, v3
	v_add3_u32 v9, 0, v3, v2
	s_waitcnt lgkmcnt(0)
	s_barrier
	ds_read2_b32 v[0:1], v8 offset1:130
	ds_read2_b32 v[2:3], v9 offset0:65 offset1:195
	v_add_u32_e32 v4, 0x400, v9
	ds_read2_b32 v[4:5], v4 offset0:69 offset1:199
	v_add_u32_e32 v6, 0x800, v9
	ds_read2_b32 v[6:7], v6 offset0:73 offset1:203
	s_waitcnt lgkmcnt(2)
	v_cvt_pk_bf16_f32 v0, v0, v2
	v_add_u32_e32 v2, 0x400, v8
	v_cvt_pk_bf16_f32 v1, v1, v3
	ds_read2_b32 v[2:3], v2 offset0:4 offset1:134
	s_waitcnt lgkmcnt(0)
	v_cvt_pk_bf16_f32 v2, v2, v4
	v_add_u32_e32 v4, 0x800, v8
	v_cvt_pk_bf16_f32 v3, v3, v5
	ds_read2_b32 v[4:5], v4 offset0:8 offset1:138
	s_waitcnt lgkmcnt(0)
	v_cvt_pk_bf16_f32 v4, v4, v6
	v_add_u32_e32 v6, 0xc00, v8
	v_add_u32_e32 v8, 0xc00, v9
	v_cvt_pk_bf16_f32 v5, v5, v7
	ds_read2_b32 v[6:7], v6 offset0:12 offset1:142
	ds_read2_b32 v[8:9], v8 offset0:77 offset1:207
	s_waitcnt lgkmcnt(0)
	v_cvt_pk_bf16_f32 v6, v6, v8
	v_add_u32_e32 v8, s38, v10
	v_cvt_pk_bf16_f32 v7, v7, v9
	v_lshlrev_b32_e32 v9, 1, v8
	v_and_b32_e32 v9, 0xffffffc0, v9
	v_and_b32_e32 v10, 31, v10
	v_or3_b32 v9, v10, s5, v9
	v_cndmask_b32_e32 v8, v9, v8, vcc
	v_ashrrev_i32_e32 v9, 31, v8
	v_lshlrev_b64 v[8:9], 11, v[8:9]
	v_lshl_add_u64 v[8:9], s[0:1], 0, v[8:9]
	s_ashr_i32 s5, s4, 31
	v_lshl_add_u64 v[8:9], s[4:5], 1, v[8:9]
	v_lshlrev_b32_e32 v10, 1, v11
	v_mov_b32_e32 v11, v96
	v_lshl_add_u64 v[8:9], v[8:9], 0, v[10:11]
	global_store_dwordx4 v[8:9], v[0:3], off
	global_store_dwordx4 v[8:9], v[4:7], off offset:16
	s_barrier
	s_branch .LBB0_1155
